# v43 minus the duplicate inline-asm vmcnt(0) wait at grid-barrier entry (subsumed by the following vmcnt(0) lgkmcnt(0))
# baseline (speedup 1.0000x reference)
.LBB0_1055:
	s_waitcnt vmcnt(0) lgkmcnt(0)
	s_barrier
	s_mov_b64 s[8:9], exec
	v_readlane_b32 s6, v253, 52
	v_readlane_b32 s7, v253, 53
	v_readlane_b32 s52, v255, 1
	v_readlane_b32 s54, v255, 3
	v_readlane_b32 s56, v255, 5
	v_readlane_b32 s58, v255, 7
	v_readlane_b32 s60, v255, 9
	v_readlane_b32 s62, v255, 11
	s_and_b64 s[6:7], s[8:9], s[6:7]
	v_readlane_b32 s53, v255, 2
	v_readlane_b32 s55, v255, 4
	v_readlane_b32 s57, v255, 6
	v_readlane_b32 s59, v255, 8
	v_readlane_b32 s61, v255, 10
	v_readlane_b32 s63, v255, 12
	v_readlane_b32 s12, v254, 42
	s_mov_b64 exec, s[6:7]
	s_cbranch_execz .LBB0_280
	v_readlane_b32 s2, v254, 50
	s_waitcnt vmcnt(0) expcnt(0) lgkmcnt(0)
	s_nop 0
	v_mov_b32_e32 v1, s2
	ds_read_b32 v3, v1
	v_readlane_b32 s2, v254, 51
	s_waitcnt lgkmcnt(0)
	v_cmp_ne_u32_e32 vcc, 0, v3
	v_mov_b32_e32 v1, s2
	ds_read_b32 v2, v1
	s_cbranch_vccnz .LBB0_1071
	s_mov_b32 s2, 1
	s_branch .LBB0_1059
